# V phase: each lane owns two adjacent output columns -> one dwordx2 load + one dwordx2 store per unit instead of 2+2 dword accesses
# speedup vs baseline: 1.0272x; 1.0272x over previous
.Lpg0_act:
	v_readlane_b32 s82, v231, 28
	v_readlane_b32 s83, v231, 29
	s_nop 4
	s_lshl_b32 s98, s2, 11
	s_add_u32 s98, s98, s101
	v_add_u32_e32 v116, s98, v234
	v_add_u32_e32 v117, 0x10000, v116
	ds_read_b32 v0, v116 offset:0
	ds_read_b32 v8, v117 offset:0
	ds_read_b32 v1, v116 offset:256
	ds_read_b32 v9, v117 offset:256
	ds_read_b32 v2, v116 offset:512
	ds_read_b32 v10, v117 offset:512
	ds_read_b32 v3, v116 offset:768
	ds_read_b32 v11, v117 offset:768
	ds_read_b32 v4, v116 offset:1024
	ds_read_b32 v12, v117 offset:1024
	ds_read_b32 v5, v116 offset:1280
	ds_read_b32 v13, v117 offset:1280
	ds_read_b32 v6, v116 offset:1536
	ds_read_b32 v14, v117 offset:1536
	ds_read_b32 v7, v116 offset:1792
	ds_read_b32 v15, v117 offset:1792
	s_waitcnt lgkmcnt(0)
	s_lshl_b32 s99, s2, 2
	s_add_u32 s99, s99, s33
	s_add_u32 s99, s99, 0
	s_lshl_b32 s99, s99, 9
	v_and_b32_e32 v0, 0x7f, v0
	v_lshl_add_u32 v0, v0, 2, s99
	global_load_dword v16, v0, s[82:83]
	v_and_b32_e32 v1, 0x7f, v1
	v_lshl_add_u32 v1, v1, 2, s99
	global_load_dword v17, v1, s[82:83]
	s_lshl_b32 s99, s2, 2
	s_add_u32 s99, s99, s33
	s_add_u32 s99, s99, 1
	s_lshl_b32 s99, s99, 9
	v_and_b32_e32 v2, 0x7f, v2
	v_lshl_add_u32 v2, v2, 2, s99
	global_load_dword v18, v2, s[82:83]
	v_and_b32_e32 v3, 0x7f, v3
	v_lshl_add_u32 v3, v3, 2, s99
	global_load_dword v19, v3, s[82:83]
	s_lshl_b32 s99, s2, 2
	s_add_u32 s99, s99, s33
	s_add_u32 s99, s99, 2
	s_lshl_b32 s99, s99, 9
	v_and_b32_e32 v4, 0x7f, v4
	v_lshl_add_u32 v4, v4, 2, s99
	global_load_dword v20, v4, s[82:83]
	v_and_b32_e32 v5, 0x7f, v5
	v_lshl_add_u32 v5, v5, 2, s99
	global_load_dword v21, v5, s[82:83]
	s_lshl_b32 s99, s2, 2
	s_add_u32 s99, s99, s33
	s_add_u32 s99, s99, 3
	s_lshl_b32 s99, s99, 9
	v_and_b32_e32 v6, 0x7f, v6
	v_lshl_add_u32 v6, v6, 2, s99
	global_load_dword v22, v6, s[82:83]
	v_and_b32_e32 v7, 0x7f, v7
	v_lshl_add_u32 v7, v7, 2, s99
	global_load_dword v23, v7, s[82:83]
	v_mul_f32_e32 v8, 0x3c800000, v8
	v_mul_f32_e32 v9, 0x3c800000, v9
	v_mul_f32_e32 v10, 0x3c800000, v10
	v_mul_f32_e32 v11, 0x3c800000, v11
	v_mul_f32_e32 v12, 0x3c800000, v12
	v_mul_f32_e32 v13, 0x3c800000, v13
	v_mul_f32_e32 v14, 0x3c800000, v14
	v_mul_f32_e32 v15, 0x3c800000, v15
	v_mul_f32_e32 v24, 0x3d372713, v8
	v_mul_f32_e32 v25, 0x3d372713, v9
	v_mul_f32_e32 v26, 0x3d372713, v10
	v_mul_f32_e32 v27, 0x3d372713, v11
	v_mul_f32_e32 v28, 0x3d372713, v12
	v_mul_f32_e32 v29, 0x3d372713, v13
	v_mul_f32_e32 v30, 0x3d372713, v14
	v_mul_f32_e32 v31, 0x3d372713, v15
	v_mul_f32_e32 v24, v8, v24
	v_mul_f32_e32 v25, v9, v25
	v_mul_f32_e32 v26, v10, v26
	v_mul_f32_e32 v27, v11, v27
	v_mul_f32_e32 v28, v12, v28
	v_mul_f32_e32 v29, v13, v29
	v_mul_f32_e32 v30, v14, v30
	v_mul_f32_e32 v31, v15, v31
	v_fma_f32 v24, v8, v24, v8
	v_fma_f32 v25, v9, v25, v9
	v_fma_f32 v26, v10, v26, v10
	v_fma_f32 v27, v11, v27, v11
	v_fma_f32 v28, v12, v28, v12
	v_fma_f32 v29, v13, v29, v13
	v_fma_f32 v30, v14, v30, v14
	v_fma_f32 v31, v15, v31, v15
	v_mul_f32_e32 v24, 0xbfcc422a, v24
	v_mul_f32_e32 v25, 0xbfcc422a, v25
	v_mul_f32_e32 v26, 0xbfcc422a, v26
	v_mul_f32_e32 v27, 0xbfcc422a, v27
	v_mul_f32_e32 v28, 0xbfcc422a, v28
	v_mul_f32_e32 v29, 0xbfcc422a, v29
	v_mul_f32_e32 v30, 0xbfcc422a, v30
	v_mul_f32_e32 v31, 0xbfcc422a, v31
	v_mul_f32_e32 v24, 0x3fb8aa3b, v24
	v_mul_f32_e32 v25, 0x3fb8aa3b, v25
	v_mul_f32_e32 v26, 0x3fb8aa3b, v26
	v_mul_f32_e32 v27, 0x3fb8aa3b, v27
	v_mul_f32_e32 v28, 0x3fb8aa3b, v28
	v_mul_f32_e32 v29, 0x3fb8aa3b, v29
	v_mul_f32_e32 v30, 0x3fb8aa3b, v30
	v_mul_f32_e32 v31, 0x3fb8aa3b, v31
	v_exp_f32_e32 v24, v24
	v_exp_f32_e32 v25, v25
	v_exp_f32_e32 v26, v26
	v_exp_f32_e32 v27, v27
	v_exp_f32_e32 v28, v28
	v_exp_f32_e32 v29, v29
	v_exp_f32_e32 v30, v30
	v_exp_f32_e32 v31, v31
	s_nop 0
	v_add_f32_e32 v24, 1.0, v24
	v_add_f32_e32 v25, 1.0, v25
	v_add_f32_e32 v26, 1.0, v26
	v_add_f32_e32 v27, 1.0, v27
	v_add_f32_e32 v28, 1.0, v28
	v_add_f32_e32 v29, 1.0, v29
	v_add_f32_e32 v30, 1.0, v30
	v_add_f32_e32 v31, 1.0, v31
	v_rcp_f32_e32 v24, v24
	v_rcp_f32_e32 v25, v25
	v_rcp_f32_e32 v26, v26
	v_rcp_f32_e32 v27, v27
	v_rcp_f32_e32 v28, v28
	v_rcp_f32_e32 v29, v29
	v_rcp_f32_e32 v30, v30
	v_rcp_f32_e32 v31, v31
	s_nop 0
	v_mul_f32_e32 v24, v8, v24
	v_mul_f32_e32 v25, v9, v25
	v_mul_f32_e32 v26, v10, v26
	v_mul_f32_e32 v27, v11, v27
	v_mul_f32_e32 v28, v12, v28
	v_mul_f32_e32 v29, v13, v29
	v_mul_f32_e32 v30, v14, v30
	v_mul_f32_e32 v31, v15, v31
	s_waitcnt vmcnt(0)
	v_mul_f32_e32 v24, v24, v16
	ds_write_b32 v117, v24 offset:0
	v_mul_f32_e32 v25, v25, v17
	ds_write_b32 v117, v25 offset:256
	v_mul_f32_e32 v26, v26, v18
	ds_write_b32 v117, v26 offset:512
	v_mul_f32_e32 v27, v27, v19
	ds_write_b32 v117, v27 offset:768
	v_mul_f32_e32 v28, v28, v20
	ds_write_b32 v117, v28 offset:1024
	v_mul_f32_e32 v29, v29, v21
	ds_write_b32 v117, v29 offset:1280
	v_mul_f32_e32 v30, v30, v22
	ds_write_b32 v117, v30 offset:1536
	v_mul_f32_e32 v31, v31, v23
	ds_write_b32 v117, v31 offset:1792
	s_add_u32 s2, s2, 1
	s_cmp_lt_u32 s2, 4
	s_cbranch_scc1 .Lpg0_act
; #define PG_ISSUE(BUF, TAB, e0_) do { const int isrc_ = ((e0_) < 64) ? myi0 : myi1; \
;       _Pragma("unroll") for (int e = 0; e < 8; ++e) { const int idx_ = __builtin_amdgcn_readlane(isrc_, ((e0_) + e) & 63); \
;         BUF[e] = *(const u32x4*)((TAB) + (size_t)idx_ * 1024 + lane * 16); } } while (0)
; DEV void peer_gather(const Params& P, int l, int m0, const int* idxs, const float* gs) {
;     ...
;     for (int e0 = 0; e0 < 128; e0 += 16) {
;       PG_ISSUE(b1, V, e0 + 8);
;       if (e0 == 64 && i + 1 < 16) sort_lists(lane, ni0, ni1, ng0, ng1);
;       PG_V16(b0, e0);
;       if (e0 + 16 < 128) PG_ISSUE(b0, V, e0 + 16);
;       PG_V16(b1, e0 + 8);
	s_waitcnt lgkmcnt(0)
	v_readfirstlane_b32 s80, v126
	v_readfirstlane_b32 s81, v127
	s_nop 4
	v_readfirstlane_b32 s82, v132
	v_readfirstlane_b32 s83, v133
	s_nop 4
	s_mov_b32 s2, 0xffffff80
	s_lshl_b32 vcc_lo, s3, 12
	s_add_u32 s82, s82, vcc_lo
	s_addc_u32 s83, s83, 0
	s_mov_b32 s88, 0xff00ff00
	s_mov_b32 s89, 0xff00ff00
	v_lshl_add_u32 v246, v237, 4, s101
	v_add_u32_e32 v247, 0x10000, v246
	v_lshlrev_b32_e32 v238, 2, v235
	v_bfe_u32 v116, v233, 5, 1
	v_lshl_add_u32 v238, v116, 3, v238
	v_bfe_u32 v116, v233, 4, 1
	v_lshl_add_u32 v238, v116, 4, v238
	v_bfe_u32 v116, v233, 3, 1
	v_lshl_add_u32 v238, v116, 5, v238
	s_mov_b32 s100, 0
	s_mov_b32 s98, 0
	s_mov_b32 s99, 0
	v_lshl_add_u32 v116, s98, 9, v246
	ds_read_b128 v[112:115], v116
	ds_read_b128 v[138:141], v116 offset:16
	ds_read_b128 v[250:253], v116 offset:32
	ds_read_b128 v[242:245], v116 offset:48
	v_lshl_or_b32 v240, s99, 21, v235
	s_waitcnt lgkmcnt(0)
	v_and_or_b32 v112, v112, s2, v240
	v_and_or_b32 v113, v113, s2, v240
	global_load_dwordx4 v[0:3], v112, s[80:81]
	global_load_dwordx4 v[4:7], v113, s[80:81]
	v_and_or_b32 v114, v114, s2, v240
	v_and_or_b32 v115, v115, s2, v240
	global_load_dwordx4 v[8:11], v114, s[80:81]
	global_load_dwordx4 v[12:15], v115, s[80:81]
	v_and_or_b32 v138, v138, s2, v240
	v_and_or_b32 v139, v139, s2, v240
	global_load_dwordx4 v[16:19], v138, s[80:81]
	global_load_dwordx4 v[20:23], v139, s[80:81]
	v_and_or_b32 v140, v140, s2, v240
	v_and_or_b32 v141, v141, s2, v240
	global_load_dwordx4 v[24:27], v140, s[80:81]
	global_load_dwordx4 v[28:31], v141, s[80:81]
	v_and_or_b32 v250, v250, s2, v240
	v_and_or_b32 v251, v251, s2, v240
	global_load_dwordx4 v[32:35], v250, s[80:81]
	global_load_dwordx4 v[36:39], v251, s[80:81]
	v_and_or_b32 v252, v252, s2, v240
	v_and_or_b32 v253, v253, s2, v240
	global_load_dwordx4 v[40:43], v252, s[80:81]
	global_load_dwordx4 v[44:47], v253, s[80:81]
	v_and_or_b32 v242, v242, s2, v240
	v_and_or_b32 v243, v243, s2, v240
	global_load_dwordx4 v[48:51], v242, s[80:81]
	global_load_dwordx4 v[52:55], v243, s[80:81]
	v_and_or_b32 v244, v244, s2, v240
	v_and_or_b32 v245, v245, s2, v240
	global_load_dwordx4 v[56:59], v244, s[80:81]
	global_load_dwordx4 v[60:63], v245, s[80:81]
	s_mov_b32 s92, 1
	v_lshl_add_u32 v116, s92, 9, v246
	ds_read_b128 v[112:115], v116
	ds_read_b128 v[138:141], v116 offset:16
	ds_read_b128 v[250:253], v116 offset:32
	ds_read_b128 v[242:245], v116 offset:48
	v_lshl_add_u32 v117, s98, 9, v247
	ds_read_b128 v[84:87], v117
	ds_read_b128 v[88:91], v117 offset:16
	ds_read_b128 v[92:95], v117 offset:32
	ds_read_b128 v[96:99], v117 offset:48
	s_waitcnt vmcnt(0)
.Lpg0_vloop:
	s_and_b32 s98, s100, 15
	s_lshr_b32 s99, s100, 4
	s_add_u32 s93, s100, 1
	s_min_u32 s93, s93, 127
	s_lshr_b32 s93, s93, 4
	s_lshl3_add_u32 vcc_lo, s98, s99
	v_lshl_add_u32 v119, vcc_lo, 9, v238
	global_load_dwordx2 v[80:81], v119, s[82:83]
	v_lshl_or_b32 v240, s93, 21, v235
	s_waitcnt lgkmcnt(0)
	s_waitcnt vmcnt(16)
	v_cvt_pk_f32_fp8_e32 v[104:105], v0
	v_cvt_pk_f32_fp8_e32 v[108:109], v4
	v_cvt_pk_f32_fp8_sdwa v[106:107], v0 src0_sel:WORD_1
	v_cvt_pk_f32_fp8_sdwa v[110:111], v4 src0_sel:WORD_1
	v_pk_mul_f32 v[64:65], v[104:105], v[84:85] op_sel_hi:[1,0]
	v_pk_mul_f32 v[66:67], v[106:107], v[84:85] op_sel_hi:[1,0]
	v_pk_fma_f32 v[64:65], v[108:109], v[84:85], v[64:65] op_sel:[0,1,0] op_sel_hi:[1,1,1]
	v_pk_fma_f32 v[66:67], v[110:111], v[84:85], v[66:67] op_sel:[0,1,0] op_sel_hi:[1,1,1]
	v_cvt_pk_f32_fp8_e32 v[104:105], v1
	v_cvt_pk_f32_fp8_e32 v[108:109], v5
	v_cvt_pk_f32_fp8_sdwa v[106:107], v1 src0_sel:WORD_1
	v_cvt_pk_f32_fp8_sdwa v[110:111], v5 src0_sel:WORD_1
	v_pk_mul_f32 v[68:69], v[104:105], v[84:85] op_sel_hi:[1,0]
	v_pk_mul_f32 v[70:71], v[106:107], v[84:85] op_sel_hi:[1,0]
	v_pk_fma_f32 v[68:69], v[108:109], v[84:85], v[68:69] op_sel:[0,1,0] op_sel_hi:[1,1,1]
	v_pk_fma_f32 v[70:71], v[110:111], v[84:85], v[70:71] op_sel:[0,1,0] op_sel_hi:[1,1,1]
	v_cvt_pk_f32_fp8_e32 v[104:105], v2
	v_cvt_pk_f32_fp8_e32 v[108:109], v6
	v_cvt_pk_f32_fp8_sdwa v[106:107], v2 src0_sel:WORD_1
	v_cvt_pk_f32_fp8_sdwa v[110:111], v6 src0_sel:WORD_1
	v_pk_mul_f32 v[72:73], v[104:105], v[84:85] op_sel_hi:[1,0]
	v_pk_mul_f32 v[74:75], v[106:107], v[84:85] op_sel_hi:[1,0]
	v_pk_fma_f32 v[72:73], v[108:109], v[84:85], v[72:73] op_sel:[0,1,0] op_sel_hi:[1,1,1]
	v_pk_fma_f32 v[74:75], v[110:111], v[84:85], v[74:75] op_sel:[0,1,0] op_sel_hi:[1,1,1]
	v_cvt_pk_f32_fp8_e32 v[104:105], v3
	v_cvt_pk_f32_fp8_e32 v[108:109], v7
	v_cvt_pk_f32_fp8_sdwa v[106:107], v3 src0_sel:WORD_1
	v_cvt_pk_f32_fp8_sdwa v[110:111], v7 src0_sel:WORD_1
	v_pk_mul_f32 v[76:77], v[104:105], v[84:85] op_sel_hi:[1,0]
	v_pk_mul_f32 v[78:79], v[106:107], v[84:85] op_sel_hi:[1,0]
	v_and_or_b32 v112, v112, s2, v240
	v_and_or_b32 v113, v113, s2, v240
	global_load_dwordx4 v[0:3], v112, s[80:81]
	global_load_dwordx4 v[4:7], v113, s[80:81]
	v_pk_fma_f32 v[76:77], v[108:109], v[84:85], v[76:77] op_sel:[0,1,0] op_sel_hi:[1,1,1]
	v_pk_fma_f32 v[78:79], v[110:111], v[84:85], v[78:79] op_sel:[0,1,0] op_sel_hi:[1,1,1]
	s_waitcnt vmcnt(16)
	v_cvt_pk_f32_fp8_e32 v[104:105], v8
	v_cvt_pk_f32_fp8_e32 v[108:109], v12
	v_cvt_pk_f32_fp8_sdwa v[106:107], v8 src0_sel:WORD_1
	v_cvt_pk_f32_fp8_sdwa v[110:111], v12 src0_sel:WORD_1
	v_pk_fma_f32 v[64:65], v[104:105], v[86:87], v[64:65] op_sel_hi:[1,0,1]
	v_pk_fma_f32 v[66:67], v[106:107], v[86:87], v[66:67] op_sel_hi:[1,0,1]
	v_pk_fma_f32 v[64:65], v[108:109], v[86:87], v[64:65] op_sel:[0,1,0] op_sel_hi:[1,1,1]
	v_pk_fma_f32 v[66:67], v[110:111], v[86:87], v[66:67] op_sel:[0,1,0] op_sel_hi:[1,1,1]
	v_cvt_pk_f32_fp8_e32 v[104:105], v9
	v_cvt_pk_f32_fp8_e32 v[108:109], v13
	v_cvt_pk_f32_fp8_sdwa v[106:107], v9 src0_sel:WORD_1
	v_cvt_pk_f32_fp8_sdwa v[110:111], v13 src0_sel:WORD_1
	v_pk_fma_f32 v[68:69], v[104:105], v[86:87], v[68:69] op_sel_hi:[1,0,1]
	v_pk_fma_f32 v[70:71], v[106:107], v[86:87], v[70:71] op_sel_hi:[1,0,1]
	v_pk_fma_f32 v[68:69], v[108:109], v[86:87], v[68:69] op_sel:[0,1,0] op_sel_hi:[1,1,1]
	v_pk_fma_f32 v[70:71], v[110:111], v[86:87], v[70:71] op_sel:[0,1,0] op_sel_hi:[1,1,1]
	v_cvt_pk_f32_fp8_e32 v[104:105], v10
	v_cvt_pk_f32_fp8_e32 v[108:109], v14
	v_cvt_pk_f32_fp8_sdwa v[106:107], v10 src0_sel:WORD_1
	v_cvt_pk_f32_fp8_sdwa v[110:111], v14 src0_sel:WORD_1
	v_pk_fma_f32 v[72:73], v[104:105], v[86:87], v[72:73] op_sel_hi:[1,0,1]
	v_pk_fma_f32 v[74:75], v[106:107], v[86:87], v[74:75] op_sel_hi:[1,0,1]
	v_pk_fma_f32 v[72:73], v[108:109], v[86:87], v[72:73] op_sel:[0,1,0] op_sel_hi:[1,1,1]
	v_pk_fma_f32 v[74:75], v[110:111], v[86:87], v[74:75] op_sel:[0,1,0] op_sel_hi:[1,1,1]
	v_cvt_pk_f32_fp8_e32 v[104:105], v11
	v_cvt_pk_f32_fp8_e32 v[108:109], v15
	v_cvt_pk_f32_fp8_sdwa v[106:107], v11 src0_sel:WORD_1
	v_cvt_pk_f32_fp8_sdwa v[110:111], v15 src0_sel:WORD_1
	v_pk_fma_f32 v[76:77], v[104:105], v[86:87], v[76:77] op_sel_hi:[1,0,1]
	v_pk_fma_f32 v[78:79], v[106:107], v[86:87], v[78:79] op_sel_hi:[1,0,1]
	v_and_or_b32 v114, v114, s2, v240
	v_and_or_b32 v115, v115, s2, v240
	global_load_dwordx4 v[8:11], v114, s[80:81]
	global_load_dwordx4 v[12:15], v115, s[80:81]
	v_pk_fma_f32 v[76:77], v[108:109], v[86:87], v[76:77] op_sel:[0,1,0] op_sel_hi:[1,1,1]
	v_pk_fma_f32 v[78:79], v[110:111], v[86:87], v[78:79] op_sel:[0,1,0] op_sel_hi:[1,1,1]
	s_waitcnt vmcnt(16)
	v_cvt_pk_f32_fp8_e32 v[104:105], v16
	v_cvt_pk_f32_fp8_e32 v[108:109], v20
	v_cvt_pk_f32_fp8_sdwa v[106:107], v16 src0_sel:WORD_1
	v_cvt_pk_f32_fp8_sdwa v[110:111], v20 src0_sel:WORD_1
	v_pk_fma_f32 v[64:65], v[104:105], v[88:89], v[64:65] op_sel_hi:[1,0,1]
	v_pk_fma_f32 v[66:67], v[106:107], v[88:89], v[66:67] op_sel_hi:[1,0,1]
	v_pk_fma_f32 v[64:65], v[108:109], v[88:89], v[64:65] op_sel:[0,1,0] op_sel_hi:[1,1,1]
	v_pk_fma_f32 v[66:67], v[110:111], v[88:89], v[66:67] op_sel:[0,1,0] op_sel_hi:[1,1,1]
	v_cvt_pk_f32_fp8_e32 v[104:105], v17
	v_cvt_pk_f32_fp8_e32 v[108:109], v21
	v_cvt_pk_f32_fp8_sdwa v[106:107], v17 src0_sel:WORD_1
	v_cvt_pk_f32_fp8_sdwa v[110:111], v21 src0_sel:WORD_1
	v_pk_fma_f32 v[68:69], v[104:105], v[88:89], v[68:69] op_sel_hi:[1,0,1]
	v_pk_fma_f32 v[70:71], v[106:107], v[88:89], v[70:71] op_sel_hi:[1,0,1]
	v_pk_fma_f32 v[68:69], v[108:109], v[88:89], v[68:69] op_sel:[0,1,0] op_sel_hi:[1,1,1]
	v_pk_fma_f32 v[70:71], v[110:111], v[88:89], v[70:71] op_sel:[0,1,0] op_sel_hi:[1,1,1]
	v_cvt_pk_f32_fp8_e32 v[104:105], v18
	v_cvt_pk_f32_fp8_e32 v[108:109], v22
	v_cvt_pk_f32_fp8_sdwa v[106:107], v18 src0_sel:WORD_1
	v_cvt_pk_f32_fp8_sdwa v[110:111], v22 src0_sel:WORD_1
	v_pk_fma_f32 v[72:73], v[104:105], v[88:89], v[72:73] op_sel_hi:[1,0,1]
	v_pk_fma_f32 v[74:75], v[106:107], v[88:89], v[74:75] op_sel_hi:[1,0,1]
	v_pk_fma_f32 v[72:73], v[108:109], v[88:89], v[72:73] op_sel:[0,1,0] op_sel_hi:[1,1,1]
	v_pk_fma_f32 v[74:75], v[110:111], v[88:89], v[74:75] op_sel:[0,1,0] op_sel_hi:[1,1,1]
	v_cvt_pk_f32_fp8_e32 v[104:105], v19
	v_cvt_pk_f32_fp8_e32 v[108:109], v23
	v_cvt_pk_f32_fp8_sdwa v[106:107], v19 src0_sel:WORD_1
	v_cvt_pk_f32_fp8_sdwa v[110:111], v23 src0_sel:WORD_1
	v_pk_fma_f32 v[76:77], v[104:105], v[88:89], v[76:77] op_sel_hi:[1,0,1]
	v_pk_fma_f32 v[78:79], v[106:107], v[88:89], v[78:79] op_sel_hi:[1,0,1]
	v_and_or_b32 v138, v138, s2, v240
	v_and_or_b32 v139, v139, s2, v240
	global_load_dwordx4 v[16:19], v138, s[80:81]
	global_load_dwordx4 v[20:23], v139, s[80:81]
	v_pk_fma_f32 v[76:77], v[108:109], v[88:89], v[76:77] op_sel:[0,1,0] op_sel_hi:[1,1,1]
	v_pk_fma_f32 v[78:79], v[110:111], v[88:89], v[78:79] op_sel:[0,1,0] op_sel_hi:[1,1,1]
	s_waitcnt vmcnt(16)
	v_cvt_pk_f32_fp8_e32 v[104:105], v24
	v_cvt_pk_f32_fp8_e32 v[108:109], v28
	v_cvt_pk_f32_fp8_sdwa v[106:107], v24 src0_sel:WORD_1
	v_cvt_pk_f32_fp8_sdwa v[110:111], v28 src0_sel:WORD_1
	v_pk_fma_f32 v[64:65], v[104:105], v[90:91], v[64:65] op_sel_hi:[1,0,1]
	v_pk_fma_f32 v[66:67], v[106:107], v[90:91], v[66:67] op_sel_hi:[1,0,1]
	v_pk_fma_f32 v[64:65], v[108:109], v[90:91], v[64:65] op_sel:[0,1,0] op_sel_hi:[1,1,1]
	v_pk_fma_f32 v[66:67], v[110:111], v[90:91], v[66:67] op_sel:[0,1,0] op_sel_hi:[1,1,1]
	v_cvt_pk_f32_fp8_e32 v[104:105], v25
	v_cvt_pk_f32_fp8_e32 v[108:109], v29
	v_cvt_pk_f32_fp8_sdwa v[106:107], v25 src0_sel:WORD_1
	v_cvt_pk_f32_fp8_sdwa v[110:111], v29 src0_sel:WORD_1
	v_pk_fma_f32 v[68:69], v[104:105], v[90:91], v[68:69] op_sel_hi:[1,0,1]
	v_pk_fma_f32 v[70:71], v[106:107], v[90:91], v[70:71] op_sel_hi:[1,0,1]
	v_pk_fma_f32 v[68:69], v[108:109], v[90:91], v[68:69] op_sel:[0,1,0] op_sel_hi:[1,1,1]
	v_pk_fma_f32 v[70:71], v[110:111], v[90:91], v[70:71] op_sel:[0,1,0] op_sel_hi:[1,1,1]
	v_cvt_pk_f32_fp8_e32 v[104:105], v26
	v_cvt_pk_f32_fp8_e32 v[108:109], v30
	v_cvt_pk_f32_fp8_sdwa v[106:107], v26 src0_sel:WORD_1
	v_cvt_pk_f32_fp8_sdwa v[110:111], v30 src0_sel:WORD_1
	v_pk_fma_f32 v[72:73], v[104:105], v[90:91], v[72:73] op_sel_hi:[1,0,1]
	v_pk_fma_f32 v[74:75], v[106:107], v[90:91], v[74:75] op_sel_hi:[1,0,1]
	v_pk_fma_f32 v[72:73], v[108:109], v[90:91], v[72:73] op_sel:[0,1,0] op_sel_hi:[1,1,1]
	v_pk_fma_f32 v[74:75], v[110:111], v[90:91], v[74:75] op_sel:[0,1,0] op_sel_hi:[1,1,1]
	v_cvt_pk_f32_fp8_e32 v[104:105], v27
	v_cvt_pk_f32_fp8_e32 v[108:109], v31
	v_cvt_pk_f32_fp8_sdwa v[106:107], v27 src0_sel:WORD_1
	v_cvt_pk_f32_fp8_sdwa v[110:111], v31 src0_sel:WORD_1
	v_pk_fma_f32 v[76:77], v[104:105], v[90:91], v[76:77] op_sel_hi:[1,0,1]
	v_pk_fma_f32 v[78:79], v[106:107], v[90:91], v[78:79] op_sel_hi:[1,0,1]
	v_and_or_b32 v140, v140, s2, v240
	v_and_or_b32 v141, v141, s2, v240
	global_load_dwordx4 v[24:27], v140, s[80:81]
	global_load_dwordx4 v[28:31], v141, s[80:81]
	v_pk_fma_f32 v[76:77], v[108:109], v[90:91], v[76:77] op_sel:[0,1,0] op_sel_hi:[1,1,1]
	v_pk_fma_f32 v[78:79], v[110:111], v[90:91], v[78:79] op_sel:[0,1,0] op_sel_hi:[1,1,1]
	s_waitcnt vmcnt(16)
	v_cvt_pk_f32_fp8_e32 v[104:105], v32
	v_cvt_pk_f32_fp8_e32 v[108:109], v36
	v_cvt_pk_f32_fp8_sdwa v[106:107], v32 src0_sel:WORD_1
	v_cvt_pk_f32_fp8_sdwa v[110:111], v36 src0_sel:WORD_1
	v_pk_fma_f32 v[64:65], v[104:105], v[92:93], v[64:65] op_sel_hi:[1,0,1]
	v_pk_fma_f32 v[66:67], v[106:107], v[92:93], v[66:67] op_sel_hi:[1,0,1]
	v_pk_fma_f32 v[64:65], v[108:109], v[92:93], v[64:65] op_sel:[0,1,0] op_sel_hi:[1,1,1]
	v_pk_fma_f32 v[66:67], v[110:111], v[92:93], v[66:67] op_sel:[0,1,0] op_sel_hi:[1,1,1]
	v_cvt_pk_f32_fp8_e32 v[104:105], v33
	v_cvt_pk_f32_fp8_e32 v[108:109], v37
	v_cvt_pk_f32_fp8_sdwa v[106:107], v33 src0_sel:WORD_1
	v_cvt_pk_f32_fp8_sdwa v[110:111], v37 src0_sel:WORD_1
	v_pk_fma_f32 v[68:69], v[104:105], v[92:93], v[68:69] op_sel_hi:[1,0,1]
	v_pk_fma_f32 v[70:71], v[106:107], v[92:93], v[70:71] op_sel_hi:[1,0,1]
	v_pk_fma_f32 v[68:69], v[108:109], v[92:93], v[68:69] op_sel:[0,1,0] op_sel_hi:[1,1,1]
	v_pk_fma_f32 v[70:71], v[110:111], v[92:93], v[70:71] op_sel:[0,1,0] op_sel_hi:[1,1,1]
	v_cvt_pk_f32_fp8_e32 v[104:105], v34
	v_cvt_pk_f32_fp8_e32 v[108:109], v38
	v_cvt_pk_f32_fp8_sdwa v[106:107], v34 src0_sel:WORD_1
	v_cvt_pk_f32_fp8_sdwa v[110:111], v38 src0_sel:WORD_1
	v_pk_fma_f32 v[72:73], v[104:105], v[92:93], v[72:73] op_sel_hi:[1,0,1]
	v_pk_fma_f32 v[74:75], v[106:107], v[92:93], v[74:75] op_sel_hi:[1,0,1]
	v_pk_fma_f32 v[72:73], v[108:109], v[92:93], v[72:73] op_sel:[0,1,0] op_sel_hi:[1,1,1]
	v_pk_fma_f32 v[74:75], v[110:111], v[92:93], v[74:75] op_sel:[0,1,0] op_sel_hi:[1,1,1]
	v_cvt_pk_f32_fp8_e32 v[104:105], v35
	v_cvt_pk_f32_fp8_e32 v[108:109], v39
	v_cvt_pk_f32_fp8_sdwa v[106:107], v35 src0_sel:WORD_1
	v_cvt_pk_f32_fp8_sdwa v[110:111], v39 src0_sel:WORD_1
	v_pk_fma_f32 v[76:77], v[104:105], v[92:93], v[76:77] op_sel_hi:[1,0,1]
	v_pk_fma_f32 v[78:79], v[106:107], v[92:93], v[78:79] op_sel_hi:[1,0,1]
	v_and_or_b32 v250, v250, s2, v240
	v_and_or_b32 v251, v251, s2, v240
	global_load_dwordx4 v[32:35], v250, s[80:81]
	global_load_dwordx4 v[36:39], v251, s[80:81]
	v_pk_fma_f32 v[76:77], v[108:109], v[92:93], v[76:77] op_sel:[0,1,0] op_sel_hi:[1,1,1]
	v_pk_fma_f32 v[78:79], v[110:111], v[92:93], v[78:79] op_sel:[0,1,0] op_sel_hi:[1,1,1]
	s_waitcnt vmcnt(16)
	v_cvt_pk_f32_fp8_e32 v[104:105], v40
	v_cvt_pk_f32_fp8_e32 v[108:109], v44
	v_cvt_pk_f32_fp8_sdwa v[106:107], v40 src0_sel:WORD_1
	v_cvt_pk_f32_fp8_sdwa v[110:111], v44 src0_sel:WORD_1
	v_pk_fma_f32 v[64:65], v[104:105], v[94:95], v[64:65] op_sel_hi:[1,0,1]
	v_pk_fma_f32 v[66:67], v[106:107], v[94:95], v[66:67] op_sel_hi:[1,0,1]
	v_pk_fma_f32 v[64:65], v[108:109], v[94:95], v[64:65] op_sel:[0,1,0] op_sel_hi:[1,1,1]
	v_pk_fma_f32 v[66:67], v[110:111], v[94:95], v[66:67] op_sel:[0,1,0] op_sel_hi:[1,1,1]
	v_cvt_pk_f32_fp8_e32 v[104:105], v41
	v_cvt_pk_f32_fp8_e32 v[108:109], v45
	v_cvt_pk_f32_fp8_sdwa v[106:107], v41 src0_sel:WORD_1
	v_cvt_pk_f32_fp8_sdwa v[110:111], v45 src0_sel:WORD_1
	v_pk_fma_f32 v[68:69], v[104:105], v[94:95], v[68:69] op_sel_hi:[1,0,1]
	v_pk_fma_f32 v[70:71], v[106:107], v[94:95], v[70:71] op_sel_hi:[1,0,1]
	v_pk_fma_f32 v[68:69], v[108:109], v[94:95], v[68:69] op_sel:[0,1,0] op_sel_hi:[1,1,1]
	v_pk_fma_f32 v[70:71], v[110:111], v[94:95], v[70:71] op_sel:[0,1,0] op_sel_hi:[1,1,1]
	v_cvt_pk_f32_fp8_e32 v[104:105], v42
	v_cvt_pk_f32_fp8_e32 v[108:109], v46
	v_cvt_pk_f32_fp8_sdwa v[106:107], v42 src0_sel:WORD_1
	v_cvt_pk_f32_fp8_sdwa v[110:111], v46 src0_sel:WORD_1
	v_pk_fma_f32 v[72:73], v[104:105], v[94:95], v[72:73] op_sel_hi:[1,0,1]
	v_pk_fma_f32 v[74:75], v[106:107], v[94:95], v[74:75] op_sel_hi:[1,0,1]
	v_pk_fma_f32 v[72:73], v[108:109], v[94:95], v[72:73] op_sel:[0,1,0] op_sel_hi:[1,1,1]
	v_pk_fma_f32 v[74:75], v[110:111], v[94:95], v[74:75] op_sel:[0,1,0] op_sel_hi:[1,1,1]
	v_cvt_pk_f32_fp8_e32 v[104:105], v43
	v_cvt_pk_f32_fp8_e32 v[108:109], v47
	v_cvt_pk_f32_fp8_sdwa v[106:107], v43 src0_sel:WORD_1
	v_cvt_pk_f32_fp8_sdwa v[110:111], v47 src0_sel:WORD_1
	v_pk_fma_f32 v[76:77], v[104:105], v[94:95], v[76:77] op_sel_hi:[1,0,1]
	v_pk_fma_f32 v[78:79], v[106:107], v[94:95], v[78:79] op_sel_hi:[1,0,1]
	v_and_or_b32 v252, v252, s2, v240
	v_and_or_b32 v253, v253, s2, v240
	global_load_dwordx4 v[40:43], v252, s[80:81]
	global_load_dwordx4 v[44:47], v253, s[80:81]
	v_pk_fma_f32 v[76:77], v[108:109], v[94:95], v[76:77] op_sel:[0,1,0] op_sel_hi:[1,1,1]
	v_pk_fma_f32 v[78:79], v[110:111], v[94:95], v[78:79] op_sel:[0,1,0] op_sel_hi:[1,1,1]
	s_waitcnt vmcnt(16)
; DEV void peer_gather(const Params& P, int l, int m0, const int* idxs, const float* gs) {
;     ...
;       hv[q][0] += acc[2 * q][0] * TAB_INV; hv[q][1] += acc[2 * q][1] * TAB_INV; hv[q][2] += acc[2 * q + 1][0] * TAB_INV; hv[q][3] += acc[2 * q + 1][1] * TAB_INV;
;       ss += hv[q][0] * hv[q][0] + hv[q][1] * hv[q][1] + hv[q][2] * hv[q][2] + hv[q][3] * hv[q][3];
;       *(f32x4*)(hrow + 4 * q) = hv[q];
	v_cvt_pk_f32_fp8_e32 v[104:105], v48
	v_cvt_pk_f32_fp8_e32 v[108:109], v52
	v_cvt_pk_f32_fp8_sdwa v[106:107], v48 src0_sel:WORD_1
	v_cvt_pk_f32_fp8_sdwa v[110:111], v52 src0_sel:WORD_1
	v_pk_fma_f32 v[64:65], v[104:105], v[96:97], v[64:65] op_sel_hi:[1,0,1]
	v_pk_fma_f32 v[66:67], v[106:107], v[96:97], v[66:67] op_sel_hi:[1,0,1]
	v_pk_fma_f32 v[64:65], v[108:109], v[96:97], v[64:65] op_sel:[0,1,0] op_sel_hi:[1,1,1]
	v_pk_fma_f32 v[66:67], v[110:111], v[96:97], v[66:67] op_sel:[0,1,0] op_sel_hi:[1,1,1]
	v_cvt_pk_f32_fp8_e32 v[104:105], v49
	v_cvt_pk_f32_fp8_e32 v[108:109], v53
	v_cvt_pk_f32_fp8_sdwa v[106:107], v49 src0_sel:WORD_1
	v_cvt_pk_f32_fp8_sdwa v[110:111], v53 src0_sel:WORD_1
	v_pk_fma_f32 v[68:69], v[104:105], v[96:97], v[68:69] op_sel_hi:[1,0,1]
	v_pk_fma_f32 v[70:71], v[106:107], v[96:97], v[70:71] op_sel_hi:[1,0,1]
	v_pk_fma_f32 v[68:69], v[108:109], v[96:97], v[68:69] op_sel:[0,1,0] op_sel_hi:[1,1,1]
	v_pk_fma_f32 v[70:71], v[110:111], v[96:97], v[70:71] op_sel:[0,1,0] op_sel_hi:[1,1,1]
	v_cvt_pk_f32_fp8_e32 v[104:105], v50
	v_cvt_pk_f32_fp8_e32 v[108:109], v54
	v_cvt_pk_f32_fp8_sdwa v[106:107], v50 src0_sel:WORD_1
	v_cvt_pk_f32_fp8_sdwa v[110:111], v54 src0_sel:WORD_1
	v_pk_fma_f32 v[72:73], v[104:105], v[96:97], v[72:73] op_sel_hi:[1,0,1]
	v_pk_fma_f32 v[74:75], v[106:107], v[96:97], v[74:75] op_sel_hi:[1,0,1]
	v_pk_fma_f32 v[72:73], v[108:109], v[96:97], v[72:73] op_sel:[0,1,0] op_sel_hi:[1,1,1]
	v_pk_fma_f32 v[74:75], v[110:111], v[96:97], v[74:75] op_sel:[0,1,0] op_sel_hi:[1,1,1]
	v_cvt_pk_f32_fp8_e32 v[104:105], v51
	v_cvt_pk_f32_fp8_e32 v[108:109], v55
	v_cvt_pk_f32_fp8_sdwa v[106:107], v51 src0_sel:WORD_1
	v_cvt_pk_f32_fp8_sdwa v[110:111], v55 src0_sel:WORD_1
	v_pk_fma_f32 v[76:77], v[104:105], v[96:97], v[76:77] op_sel_hi:[1,0,1]
	v_pk_fma_f32 v[78:79], v[106:107], v[96:97], v[78:79] op_sel_hi:[1,0,1]
	v_and_or_b32 v242, v242, s2, v240
	v_and_or_b32 v243, v243, s2, v240
	global_load_dwordx4 v[48:51], v242, s[80:81]
	global_load_dwordx4 v[52:55], v243, s[80:81]
	v_pk_fma_f32 v[76:77], v[108:109], v[96:97], v[76:77] op_sel:[0,1,0] op_sel_hi:[1,1,1]
	v_pk_fma_f32 v[78:79], v[110:111], v[96:97], v[78:79] op_sel:[0,1,0] op_sel_hi:[1,1,1]
	s_waitcnt vmcnt(16)
	v_cvt_pk_f32_fp8_e32 v[104:105], v56
	v_cvt_pk_f32_fp8_e32 v[108:109], v60
	v_cvt_pk_f32_fp8_sdwa v[106:107], v56 src0_sel:WORD_1
	v_cvt_pk_f32_fp8_sdwa v[110:111], v60 src0_sel:WORD_1
	v_pk_fma_f32 v[64:65], v[104:105], v[98:99], v[64:65] op_sel_hi:[1,0,1]
	v_pk_fma_f32 v[66:67], v[106:107], v[98:99], v[66:67] op_sel_hi:[1,0,1]
	v_pk_fma_f32 v[64:65], v[108:109], v[98:99], v[64:65] op_sel:[0,1,0] op_sel_hi:[1,1,1]
	v_pk_fma_f32 v[66:67], v[110:111], v[98:99], v[66:67] op_sel:[0,1,0] op_sel_hi:[1,1,1]
	v_cvt_pk_f32_fp8_e32 v[104:105], v57
	v_cvt_pk_f32_fp8_e32 v[108:109], v61
	v_cvt_pk_f32_fp8_sdwa v[106:107], v57 src0_sel:WORD_1
	v_cvt_pk_f32_fp8_sdwa v[110:111], v61 src0_sel:WORD_1
	v_pk_fma_f32 v[68:69], v[104:105], v[98:99], v[68:69] op_sel_hi:[1,0,1]
	v_pk_fma_f32 v[70:71], v[106:107], v[98:99], v[70:71] op_sel_hi:[1,0,1]
	v_pk_fma_f32 v[68:69], v[108:109], v[98:99], v[68:69] op_sel:[0,1,0] op_sel_hi:[1,1,1]
	v_pk_fma_f32 v[70:71], v[110:111], v[98:99], v[70:71] op_sel:[0,1,0] op_sel_hi:[1,1,1]
	v_cvt_pk_f32_fp8_e32 v[104:105], v58
	v_cvt_pk_f32_fp8_e32 v[108:109], v62
	v_cvt_pk_f32_fp8_sdwa v[106:107], v58 src0_sel:WORD_1
	v_cvt_pk_f32_fp8_sdwa v[110:111], v62 src0_sel:WORD_1
	v_pk_fma_f32 v[72:73], v[104:105], v[98:99], v[72:73] op_sel_hi:[1,0,1]
	v_pk_fma_f32 v[74:75], v[106:107], v[98:99], v[74:75] op_sel_hi:[1,0,1]
	v_pk_fma_f32 v[72:73], v[108:109], v[98:99], v[72:73] op_sel:[0,1,0] op_sel_hi:[1,1,1]
	v_pk_fma_f32 v[74:75], v[110:111], v[98:99], v[74:75] op_sel:[0,1,0] op_sel_hi:[1,1,1]
	v_cvt_pk_f32_fp8_e32 v[104:105], v59
	v_cvt_pk_f32_fp8_e32 v[108:109], v63
	v_cvt_pk_f32_fp8_sdwa v[106:107], v59 src0_sel:WORD_1
	v_cvt_pk_f32_fp8_sdwa v[110:111], v63 src0_sel:WORD_1
	v_pk_fma_f32 v[76:77], v[104:105], v[98:99], v[76:77] op_sel_hi:[1,0,1]
	v_pk_fma_f32 v[78:79], v[106:107], v[98:99], v[78:79] op_sel_hi:[1,0,1]
	v_and_or_b32 v244, v244, s2, v240
	v_and_or_b32 v245, v245, s2, v240
	global_load_dwordx4 v[56:59], v244, s[80:81]
	global_load_dwordx4 v[60:63], v245, s[80:81]
	v_pk_fma_f32 v[76:77], v[108:109], v[98:99], v[76:77] op_sel:[0,1,0] op_sel_hi:[1,1,1]
	v_pk_fma_f32 v[78:79], v[110:111], v[98:99], v[78:79] op_sel:[0,1,0] op_sel_hi:[1,1,1]
	s_add_u32 s92, s100, 2
	s_and_b32 s92, s92, 15
	v_lshl_add_u32 v116, s92, 9, v246
	ds_read_b128 v[112:115], v116
	ds_read_b128 v[138:141], v116 offset:16
	ds_read_b128 v[250:253], v116 offset:32
	ds_read_b128 v[242:245], v116 offset:48
	s_add_u32 s92, s100, 1
	s_and_b32 s92, s92, 15
	v_lshl_add_u32 v117, s92, 9, v247
	ds_read_b128 v[84:87], v117
	ds_read_b128 v[88:91], v117 offset:16
	ds_read_b128 v[92:95], v117 offset:32
	ds_read_b128 v[96:99], v117 offset:48
	s_nop 1
	v_permlane32_swap_b32_e32 v64, v66
	v_permlane32_swap_b32_e32 v65, v67
	v_permlane32_swap_b32_e32 v68, v70
	v_permlane32_swap_b32_e32 v69, v71
	v_permlane32_swap_b32_e32 v72, v74
	v_permlane32_swap_b32_e32 v73, v75
	v_permlane32_swap_b32_e32 v76, v78
	v_permlane32_swap_b32_e32 v77, v79
	v_add_f32_e32 v64, v64, v66
	v_add_f32_e32 v65, v65, v67
	v_add_f32_e32 v68, v68, v70
	v_add_f32_e32 v69, v69, v71
	v_add_f32_e32 v72, v72, v74
	v_add_f32_e32 v73, v73, v75
	v_add_f32_e32 v76, v76, v78
	v_add_f32_e32 v77, v77, v79
	s_nop 1
	v_permlane16_swap_b32_e32 v64, v68
	v_permlane16_swap_b32_e32 v65, v69
	v_permlane16_swap_b32_e32 v72, v76
	v_permlane16_swap_b32_e32 v73, v77
	v_add_f32_e32 v64, v64, v68
	v_add_f32_e32 v65, v65, v69
	v_add_f32_e32 v72, v72, v76
	v_add_f32_e32 v73, v73, v77
	s_nop 0
	v_cndmask_b32_e64 v66, v64, v72, s[88:89]
	v_cndmask_b32_e64 v67, v72, v64, s[88:89]
	v_cndmask_b32_e64 v74, v65, v73, s[88:89]
	v_cndmask_b32_e64 v75, v73, v65, s[88:89]
	s_nop 1
	v_add_f32_dpp v64, v67, v66 row_ror:8 row_mask:0xf bank_mask:0xf
	v_add_f32_dpp v65, v75, v74 row_ror:8 row_mask:0xf bank_mask:0xf
	s_waitcnt vmcnt(16)
	v_fmac_f32_e32 v80, 0x3c800000, v64
	v_fmac_f32_e32 v81, 0x3c800000, v65
	global_store_dwordx2 v119, v[80:81], s[82:83]
	s_add_u32 s100, s100, 1
	s_cmp_lt_u32 s100, 128
	s_cbranch_scc1 .Lpg0_vloop
	s_waitcnt vmcnt(0) lgkmcnt(0)
	v_readfirstlane_b32 s88, v130
	v_readfirstlane_b32 s89, v131
	s_nop 4
	v_lshlrev_b32_e32 v117, 6, v233
	global_load_dwordx4 v[16:19], v117, s[88:89] offset:0
	global_load_dwordx4 v[20:23], v117, s[88:89] offset:16
	global_load_dwordx4 v[24:27], v117, s[88:89] offset:32
	global_load_dwordx4 v[28:31], v117, s[88:89] offset:48
	s_mov_b32 s2, 0

.Lpg1_act:
	v_readlane_b32 s82, v232, 1
	v_readlane_b32 s83, v232, 2
	s_nop 4
	s_lshl_b32 s98, s2, 11
	s_add_u32 s98, s98, s101
	v_add_u32_e32 v116, s98, v234
	v_add_u32_e32 v117, 0x10000, v116
	ds_read_b32 v0, v116 offset:0
	ds_read_b32 v8, v117 offset:0
	ds_read_b32 v1, v116 offset:256
	ds_read_b32 v9, v117 offset:256
	ds_read_b32 v2, v116 offset:512
	ds_read_b32 v10, v117 offset:512
	ds_read_b32 v3, v116 offset:768
	ds_read_b32 v11, v117 offset:768
	ds_read_b32 v4, v116 offset:1024
	ds_read_b32 v12, v117 offset:1024
	ds_read_b32 v5, v116 offset:1280
	ds_read_b32 v13, v117 offset:1280
	ds_read_b32 v6, v116 offset:1536
	ds_read_b32 v14, v117 offset:1536
	ds_read_b32 v7, v116 offset:1792
	ds_read_b32 v15, v117 offset:1792
	s_waitcnt lgkmcnt(0)
	s_lshl_b32 s99, s2, 2
	s_add_u32 s99, s99, s33
	s_add_u32 s99, s99, 0
	s_lshl_b32 s99, s99, 9
	v_and_b32_e32 v0, 0x7f, v0
	v_lshl_add_u32 v0, v0, 2, s99
	global_load_dword v16, v0, s[82:83]
	v_and_b32_e32 v1, 0x7f, v1
	v_lshl_add_u32 v1, v1, 2, s99
	global_load_dword v17, v1, s[82:83]
	s_lshl_b32 s99, s2, 2
	s_add_u32 s99, s99, s33
	s_add_u32 s99, s99, 1
	s_lshl_b32 s99, s99, 9
	v_and_b32_e32 v2, 0x7f, v2
	v_lshl_add_u32 v2, v2, 2, s99
	global_load_dword v18, v2, s[82:83]
	v_and_b32_e32 v3, 0x7f, v3
	v_lshl_add_u32 v3, v3, 2, s99
	global_load_dword v19, v3, s[82:83]
	s_lshl_b32 s99, s2, 2
	s_add_u32 s99, s99, s33
	s_add_u32 s99, s99, 2
	s_lshl_b32 s99, s99, 9
	v_and_b32_e32 v4, 0x7f, v4
	v_lshl_add_u32 v4, v4, 2, s99
	global_load_dword v20, v4, s[82:83]
	v_and_b32_e32 v5, 0x7f, v5
	v_lshl_add_u32 v5, v5, 2, s99
	global_load_dword v21, v5, s[82:83]
	s_lshl_b32 s99, s2, 2
	s_add_u32 s99, s99, s33
	s_add_u32 s99, s99, 3
	s_lshl_b32 s99, s99, 9
	v_and_b32_e32 v6, 0x7f, v6
	v_lshl_add_u32 v6, v6, 2, s99
	global_load_dword v22, v6, s[82:83]
	v_and_b32_e32 v7, 0x7f, v7
	v_lshl_add_u32 v7, v7, 2, s99
	global_load_dword v23, v7, s[82:83]
	v_mul_f32_e32 v8, 0x3c800000, v8
	v_mul_f32_e32 v9, 0x3c800000, v9
	v_mul_f32_e32 v10, 0x3c800000, v10
	v_mul_f32_e32 v11, 0x3c800000, v11
	v_mul_f32_e32 v12, 0x3c800000, v12
	v_mul_f32_e32 v13, 0x3c800000, v13
	v_mul_f32_e32 v14, 0x3c800000, v14
	v_mul_f32_e32 v15, 0x3c800000, v15
	v_mul_f32_e32 v24, 0x3d372713, v8
	v_mul_f32_e32 v25, 0x3d372713, v9
	v_mul_f32_e32 v26, 0x3d372713, v10
	v_mul_f32_e32 v27, 0x3d372713, v11
	v_mul_f32_e32 v28, 0x3d372713, v12
	v_mul_f32_e32 v29, 0x3d372713, v13
	v_mul_f32_e32 v30, 0x3d372713, v14
	v_mul_f32_e32 v31, 0x3d372713, v15
	v_mul_f32_e32 v24, v8, v24
	v_mul_f32_e32 v25, v9, v25
	v_mul_f32_e32 v26, v10, v26
	v_mul_f32_e32 v27, v11, v27
	v_mul_f32_e32 v28, v12, v28
	v_mul_f32_e32 v29, v13, v29
	v_mul_f32_e32 v30, v14, v30
	v_mul_f32_e32 v31, v15, v31
	v_fma_f32 v24, v8, v24, v8
	v_fma_f32 v25, v9, v25, v9
	v_fma_f32 v26, v10, v26, v10
	v_fma_f32 v27, v11, v27, v11
	v_fma_f32 v28, v12, v28, v12
	v_fma_f32 v29, v13, v29, v13
	v_fma_f32 v30, v14, v30, v14
	v_fma_f32 v31, v15, v31, v15
	v_mul_f32_e32 v24, 0xbfcc422a, v24
	v_mul_f32_e32 v25, 0xbfcc422a, v25
	v_mul_f32_e32 v26, 0xbfcc422a, v26
	v_mul_f32_e32 v27, 0xbfcc422a, v27
	v_mul_f32_e32 v28, 0xbfcc422a, v28
	v_mul_f32_e32 v29, 0xbfcc422a, v29
	v_mul_f32_e32 v30, 0xbfcc422a, v30
	v_mul_f32_e32 v31, 0xbfcc422a, v31
	v_mul_f32_e32 v24, 0x3fb8aa3b, v24
	v_mul_f32_e32 v25, 0x3fb8aa3b, v25
	v_mul_f32_e32 v26, 0x3fb8aa3b, v26
	v_mul_f32_e32 v27, 0x3fb8aa3b, v27
	v_mul_f32_e32 v28, 0x3fb8aa3b, v28
	v_mul_f32_e32 v29, 0x3fb8aa3b, v29
	v_mul_f32_e32 v30, 0x3fb8aa3b, v30
	v_mul_f32_e32 v31, 0x3fb8aa3b, v31
	v_exp_f32_e32 v24, v24
	v_exp_f32_e32 v25, v25
	v_exp_f32_e32 v26, v26
	v_exp_f32_e32 v27, v27
	v_exp_f32_e32 v28, v28
	v_exp_f32_e32 v29, v29
	v_exp_f32_e32 v30, v30
	v_exp_f32_e32 v31, v31
	s_nop 0
	v_add_f32_e32 v24, 1.0, v24
	v_add_f32_e32 v25, 1.0, v25
	v_add_f32_e32 v26, 1.0, v26
	v_add_f32_e32 v27, 1.0, v27
	v_add_f32_e32 v28, 1.0, v28
	v_add_f32_e32 v29, 1.0, v29
	v_add_f32_e32 v30, 1.0, v30
	v_add_f32_e32 v31, 1.0, v31
	v_rcp_f32_e32 v24, v24
	v_rcp_f32_e32 v25, v25
	v_rcp_f32_e32 v26, v26
	v_rcp_f32_e32 v27, v27
	v_rcp_f32_e32 v28, v28
	v_rcp_f32_e32 v29, v29
	v_rcp_f32_e32 v30, v30
	v_rcp_f32_e32 v31, v31
	s_nop 0
	v_mul_f32_e32 v24, v8, v24
	v_mul_f32_e32 v25, v9, v25
	v_mul_f32_e32 v26, v10, v26
	v_mul_f32_e32 v27, v11, v27
	v_mul_f32_e32 v28, v12, v28
	v_mul_f32_e32 v29, v13, v29
	v_mul_f32_e32 v30, v14, v30
	v_mul_f32_e32 v31, v15, v31
	s_waitcnt vmcnt(0)
	v_mul_f32_e32 v24, v24, v16
	ds_write_b32 v117, v24 offset:0
	v_mul_f32_e32 v25, v25, v17
	ds_write_b32 v117, v25 offset:256
	v_mul_f32_e32 v26, v26, v18
	ds_write_b32 v117, v26 offset:512
	v_mul_f32_e32 v27, v27, v19
	ds_write_b32 v117, v27 offset:768
	v_mul_f32_e32 v28, v28, v20
	ds_write_b32 v117, v28 offset:1024
	v_mul_f32_e32 v29, v29, v21
	ds_write_b32 v117, v29 offset:1280
	v_mul_f32_e32 v30, v30, v22
	ds_write_b32 v117, v30 offset:1536
	v_mul_f32_e32 v31, v31, v23
	ds_write_b32 v117, v31 offset:1792
	s_add_u32 s2, s2, 1
	s_cmp_lt_u32 s2, 4
	s_cbranch_scc1 .Lpg1_act
; #define PG_ISSUE(BUF, TAB, e0_) do { const int isrc_ = ((e0_) < 64) ? myi0 : myi1; \
;       _Pragma("unroll") for (int e = 0; e < 8; ++e) { const int idx_ = __builtin_amdgcn_readlane(isrc_, ((e0_) + e) & 63); \
;         BUF[e] = *(const u32x4*)((TAB) + (size_t)idx_ * 1024 + lane * 16); } } while (0)
; DEV void peer_gather(const Params& P, int l, int m0, const int* idxs, const float* gs) {
;     ...
;     for (int e0 = 0; e0 < 128; e0 += 16) {
;       PG_ISSUE(b1, V, e0 + 8);
;       if (e0 == 64 && i + 1 < 16) sort_lists(lane, ni0, ni1, ng0, ng1);
;       PG_V16(b0, e0);
;       if (e0 + 16 < 128) PG_ISSUE(b0, V, e0 + 16);
	s_waitcnt lgkmcnt(0)
	v_readfirstlane_b32 s80, v128
	v_readfirstlane_b32 s81, v129
	s_nop 4
	v_readfirstlane_b32 s82, v132
	v_readfirstlane_b32 s83, v133
	s_nop 4
	s_mov_b32 s2, 0xffffff80
	s_lshl_b32 vcc_lo, s3, 12
	s_add_u32 s82, s82, vcc_lo
	s_addc_u32 s83, s83, 0
	s_mov_b32 s88, 0xff00ff00
	s_mov_b32 s89, 0xff00ff00
	v_lshl_add_u32 v246, v237, 4, s101
	v_add_u32_e32 v247, 0x10000, v246
	v_lshlrev_b32_e32 v238, 2, v235
	v_bfe_u32 v116, v233, 5, 1
	v_lshl_add_u32 v238, v116, 3, v238
	v_bfe_u32 v116, v233, 4, 1
	v_lshl_add_u32 v238, v116, 4, v238
	v_bfe_u32 v116, v233, 3, 1
	v_lshl_add_u32 v238, v116, 5, v238
	s_mov_b32 s100, 0
	s_mov_b32 s98, 0
	s_mov_b32 s99, 0
	v_lshl_add_u32 v116, s98, 9, v246
	ds_read_b128 v[112:115], v116
	ds_read_b128 v[138:141], v116 offset:16
	ds_read_b128 v[250:253], v116 offset:32
	ds_read_b128 v[242:245], v116 offset:48
	v_lshl_or_b32 v240, s99, 21, v235
	s_waitcnt lgkmcnt(0)
	v_and_or_b32 v112, v112, s2, v240
	v_and_or_b32 v113, v113, s2, v240
	global_load_dwordx4 v[0:3], v112, s[80:81]
	global_load_dwordx4 v[4:7], v113, s[80:81]
	v_and_or_b32 v114, v114, s2, v240
	v_and_or_b32 v115, v115, s2, v240
	global_load_dwordx4 v[8:11], v114, s[80:81]
	global_load_dwordx4 v[12:15], v115, s[80:81]
	v_and_or_b32 v138, v138, s2, v240
	v_and_or_b32 v139, v139, s2, v240
	global_load_dwordx4 v[16:19], v138, s[80:81]
	global_load_dwordx4 v[20:23], v139, s[80:81]
	v_and_or_b32 v140, v140, s2, v240
	v_and_or_b32 v141, v141, s2, v240
	global_load_dwordx4 v[24:27], v140, s[80:81]
	global_load_dwordx4 v[28:31], v141, s[80:81]
	v_and_or_b32 v250, v250, s2, v240
	v_and_or_b32 v251, v251, s2, v240
	global_load_dwordx4 v[32:35], v250, s[80:81]
	global_load_dwordx4 v[36:39], v251, s[80:81]
	v_and_or_b32 v252, v252, s2, v240
	v_and_or_b32 v253, v253, s2, v240
	global_load_dwordx4 v[40:43], v252, s[80:81]
	global_load_dwordx4 v[44:47], v253, s[80:81]
	v_and_or_b32 v242, v242, s2, v240
	v_and_or_b32 v243, v243, s2, v240
	global_load_dwordx4 v[48:51], v242, s[80:81]
	global_load_dwordx4 v[52:55], v243, s[80:81]
	v_and_or_b32 v244, v244, s2, v240
	v_and_or_b32 v245, v245, s2, v240
	global_load_dwordx4 v[56:59], v244, s[80:81]
	global_load_dwordx4 v[60:63], v245, s[80:81]
	s_mov_b32 s92, 1
	v_lshl_add_u32 v116, s92, 9, v246
	ds_read_b128 v[112:115], v116
	ds_read_b128 v[138:141], v116 offset:16
	ds_read_b128 v[250:253], v116 offset:32
	ds_read_b128 v[242:245], v116 offset:48
	v_lshl_add_u32 v117, s98, 9, v247
	ds_read_b128 v[84:87], v117
	ds_read_b128 v[88:91], v117 offset:16
	ds_read_b128 v[92:95], v117 offset:32
	ds_read_b128 v[96:99], v117 offset:48
	s_waitcnt vmcnt(0)
